# removed compiler-inserted vmcnt(0) drain inside gate_up K-loop (not part of the source schedule)
# speedup vs baseline: 1.0218x; 1.0103x over previous
.LBB0_98:
	s_add_u32 s18, s44, 0xfffc0080
	s_addc_u32 s19, s45, -1
	s_add_i32 s46, 0, 0x10000
	s_cmp_eq_u32 s15, 12
	s_cselect_b32 s25, s7, s19
	s_cselect_b32 s24, s10, s18
	v_add_u32_e32 v148, s46, v150
	s_cselect_b32 s23, s5, s14
	s_cselect_b32 s22, s11, s13
	s_add_i32 s47, 0, 0x14000
	ds_read_b128 v[156:159], v148
	ds_read_b128 v[160:163], v148 offset:1024
	ds_read_b128 v[164:167], v148 offset:2048
	ds_read_b128 v[168:171], v148 offset:3072
	v_add_u32_e32 v148, s47, v150
	ds_read_b128 v[172:175], v148
	ds_read_b128 v[176:179], v148 offset:1024
	ds_read_b128 v[180:183], v148 offset:2048
	ds_read_b128 v[184:187], v148 offset:3072
	v_lshl_add_u64 v[148:149], s[44:45], 0, v[144:145]
	s_add_i32 m0, s29, 0xc000
	ds_read_b128 v[208:211], v155
	ds_read_b128 v[212:215], v155 offset:1024
	ds_read_b128 v[216:219], v155 offset:2048
	ds_read_b128 v[220:223], v155 offset:3072
	ds_read_b128 v[224:227], v155 offset:4096
	ds_read_b128 v[228:231], v155 offset:5120
	ds_read_b128 v[232:235], v155 offset:6144
	ds_read_b128 v[236:239], v155 offset:7168
	global_load_lds_dwordx4 v[148:149], off
	v_lshl_add_u64 v[148:149], s[44:45], 0, v[146:147]
	s_add_i32 m0, s29, 0xe000
	s_nop 0
	global_load_lds_dwordx4 v[148:149], off
	s_waitcnt vmcnt(8)
	s_waitcnt lgkmcnt(0)
	s_barrier
	s_setprio 1
	s_waitcnt lgkmcnt(0)
	v_mfma_f32_16x16x32_bf16 v[128:131], v[156:159], v[208:211], v[128:131]
	v_mfma_f32_16x16x32_bf16 v[120:123], v[164:167], v[208:211], v[120:123]
	v_mfma_f32_16x16x32_bf16 v[112:115], v[156:159], v[216:219], v[112:115]
	v_mfma_f32_16x16x32_bf16 v[104:107], v[164:167], v[216:219], v[104:107]
	v_mfma_f32_16x16x32_bf16 v[96:99], v[156:159], v[224:227], v[96:99]
	v_mfma_f32_16x16x32_bf16 v[88:91], v[164:167], v[224:227], v[88:91]
	v_mfma_f32_16x16x32_bf16 v[80:83], v[156:159], v[232:235], v[80:83]
	v_mfma_f32_16x16x32_bf16 v[72:75], v[164:167], v[232:235], v[72:75]
	v_mfma_f32_16x16x32_bf16 v[128:131], v[160:163], v[212:215], v[128:131]
	v_mfma_f32_16x16x32_bf16 v[120:123], v[168:171], v[212:215], v[120:123]
	v_mfma_f32_16x16x32_bf16 v[112:115], v[160:163], v[220:223], v[112:115]
	v_mfma_f32_16x16x32_bf16 v[104:107], v[168:171], v[220:223], v[104:107]
	v_mfma_f32_16x16x32_bf16 v[96:99], v[160:163], v[228:231], v[96:99]
	v_mfma_f32_16x16x32_bf16 v[88:91], v[168:171], v[228:231], v[88:91]
	v_mfma_f32_16x16x32_bf16 v[80:83], v[160:163], v[236:239], v[80:83]
	v_mfma_f32_16x16x32_bf16 v[72:75], v[168:171], v[236:239], v[72:75]
	s_setprio 0
	s_setprio 1
	v_mfma_f32_16x16x32_bf16 v[124:127], v[172:175], v[208:211], v[124:127]
	v_mfma_f32_16x16x32_bf16 v[116:119], v[180:183], v[208:211], v[116:119]
	v_mfma_f32_16x16x32_bf16 v[108:111], v[172:175], v[216:219], v[108:111]
	v_mfma_f32_16x16x32_bf16 v[100:103], v[180:183], v[216:219], v[100:103]
	v_mfma_f32_16x16x32_bf16 v[92:95], v[172:175], v[224:227], v[92:95]
	v_mfma_f32_16x16x32_bf16 v[84:87], v[180:183], v[224:227], v[84:87]
	v_mfma_f32_16x16x32_bf16 v[76:79], v[172:175], v[232:235], v[76:79]
	v_mfma_f32_16x16x32_bf16 v[68:71], v[180:183], v[232:235], v[68:71]
	v_mfma_f32_16x16x32_bf16 v[124:127], v[176:179], v[212:215], v[124:127]
	v_mfma_f32_16x16x32_bf16 v[116:119], v[184:187], v[212:215], v[116:119]
	v_mfma_f32_16x16x32_bf16 v[108:111], v[176:179], v[220:223], v[108:111]
	v_mfma_f32_16x16x32_bf16 v[100:103], v[184:187], v[220:223], v[100:103]
	v_mfma_f32_16x16x32_bf16 v[92:95], v[176:179], v[228:231], v[92:95]
	v_mfma_f32_16x16x32_bf16 v[84:87], v[184:187], v[228:231], v[84:87]
	v_mfma_f32_16x16x32_bf16 v[76:79], v[176:179], v[236:239], v[76:79]
	v_mfma_f32_16x16x32_bf16 v[68:71], v[184:187], v[236:239], v[68:71]
	s_setprio 0
	s_barrier
	s_add_i32 s18, s46, s28
	v_lshl_add_u64 v[148:149], s[22:23], 0, v[2:3]
	s_mov_b32 m0, s18
	ds_read_b128 v[208:211], v155 offset:16384
	ds_read_b128 v[212:215], v155 offset:17408
	ds_read_b128 v[216:219], v155 offset:18432
	ds_read_b128 v[220:223], v155 offset:19456
	ds_read_b128 v[224:227], v155 offset:20480
	ds_read_b128 v[228:231], v155 offset:21504
	ds_read_b128 v[232:235], v155 offset:22528
	ds_read_b128 v[236:239], v155 offset:23552
	global_load_lds_dwordx4 v[148:149], off
	s_add_i32 m0, s18, 0x2000
	s_add_u32 s18, s22, 0x40000
	v_lshl_add_u64 v[188:189], s[22:23], 0, v[142:143]
	s_addc_u32 s19, s23, 0
	s_add_i32 s46, s47, s28
	global_load_lds_dwordx4 v[188:189], off
	v_lshl_add_u64 v[196:197], s[18:19], 0, v[2:3]
	s_mov_b32 m0, s46
	v_lshl_add_u64 v[198:199], s[24:25], 0, v[140:141]
	global_load_lds_dwordx4 v[196:197], off
	v_lshl_add_u64 v[196:197], s[18:19], 0, v[142:143]
	s_add_i32 m0, s46, 0x2000
	s_nop 0
	global_load_lds_dwordx4 v[196:197], off
	v_lshl_add_u64 v[196:197], s[24:25], 0, v[0:1]
	s_mov_b32 m0, s29
	s_nop 0
	global_load_lds_dwordx4 v[196:197], off
	s_mov_b32 m0, s43
	s_nop 0
	global_load_lds_dwordx4 v[198:199], off
	s_waitcnt vmcnt(8)
	s_waitcnt lgkmcnt(0)
	s_barrier
	s_setprio 1
	s_waitcnt lgkmcnt(0)
	v_mfma_f32_16x16x32_bf16 v[64:67], v[156:159], v[208:211], v[64:67]
	v_mfma_f32_16x16x32_bf16 v[56:59], v[164:167], v[208:211], v[56:59]
	v_mfma_f32_16x16x32_bf16 v[48:51], v[156:159], v[216:219], v[48:51]
	v_mfma_f32_16x16x32_bf16 v[40:43], v[164:167], v[216:219], v[40:43]
	v_mfma_f32_16x16x32_bf16 v[32:35], v[156:159], v[224:227], v[32:35]
	v_mfma_f32_16x16x32_bf16 v[24:27], v[164:167], v[224:227], v[24:27]
	v_mfma_f32_16x16x32_bf16 v[16:19], v[156:159], v[232:235], v[16:19]
	v_mfma_f32_16x16x32_bf16 v[8:11], v[164:167], v[232:235], v[8:11]
	v_mfma_f32_16x16x32_bf16 v[64:67], v[160:163], v[212:215], v[64:67]
	v_mfma_f32_16x16x32_bf16 v[56:59], v[168:171], v[212:215], v[56:59]
	v_mfma_f32_16x16x32_bf16 v[48:51], v[160:163], v[220:223], v[48:51]
	v_mfma_f32_16x16x32_bf16 v[40:43], v[168:171], v[220:223], v[40:43]
	v_mfma_f32_16x16x32_bf16 v[32:35], v[160:163], v[228:231], v[32:35]
	v_mfma_f32_16x16x32_bf16 v[24:27], v[168:171], v[228:231], v[24:27]
	v_mfma_f32_16x16x32_bf16 v[16:19], v[160:163], v[236:239], v[16:19]
	v_mfma_f32_16x16x32_bf16 v[8:11], v[168:171], v[236:239], v[8:11]
	s_setprio 0
	s_setprio 1
	v_mfma_f32_16x16x32_bf16 v[60:63], v[172:175], v[208:211], v[60:63]
	v_mfma_f32_16x16x32_bf16 v[52:55], v[180:183], v[208:211], v[52:55]
	v_mfma_f32_16x16x32_bf16 v[44:47], v[172:175], v[216:219], v[44:47]
	v_mfma_f32_16x16x32_bf16 v[36:39], v[180:183], v[216:219], v[36:39]
	v_mfma_f32_16x16x32_bf16 v[28:31], v[172:175], v[224:227], v[28:31]
	v_mfma_f32_16x16x32_bf16 v[20:23], v[180:183], v[224:227], v[20:23]
	v_mfma_f32_16x16x32_bf16 v[12:15], v[172:175], v[232:235], v[12:15]
	v_mfma_f32_16x16x32_bf16 v[4:7], v[180:183], v[232:235], v[4:7]
	v_mfma_f32_16x16x32_bf16 v[60:63], v[176:179], v[212:215], v[60:63]
	v_mfma_f32_16x16x32_bf16 v[52:55], v[184:187], v[212:215], v[52:55]
	v_mfma_f32_16x16x32_bf16 v[44:47], v[176:179], v[220:223], v[44:47]
	v_mfma_f32_16x16x32_bf16 v[36:39], v[184:187], v[220:223], v[36:39]
	v_mfma_f32_16x16x32_bf16 v[28:31], v[176:179], v[228:231], v[28:31]
	v_mfma_f32_16x16x32_bf16 v[20:23], v[184:187], v[228:231], v[20:23]
	v_mfma_f32_16x16x32_bf16 v[12:15], v[176:179], v[236:239], v[12:15]
	v_mfma_f32_16x16x32_bf16 v[4:7], v[184:187], v[236:239], v[4:7]
	s_setprio 0
	s_barrier
	s_add_i32 s46, 0, 0x18000
	s_add_i32 s47, 0, 0x1c000
	v_add_u32_e32 v168, s46, v150
	v_add_u32_e32 v184, s47, v150
	ds_read_b128 v[156:159], v168
	ds_read_b128 v[160:163], v168 offset:1024
	ds_read_b128 v[164:167], v168 offset:2048
	ds_read_b128 v[168:171], v168 offset:3072
	ds_read_b128 v[172:175], v184
	ds_read_b128 v[176:179], v184 offset:1024
	ds_read_b128 v[180:183], v184 offset:2048
	ds_read_b128 v[184:187], v184 offset:3072
	s_add_u32 s18, s24, 0x40000
	s_addc_u32 s19, s25, 0
	s_mov_b32 m0, s48
	v_lshl_add_u64 v[200:201], s[18:19], 0, v[0:1]
	ds_read_b128 v[208:211], v155 offset:32768
	ds_read_b128 v[212:215], v155 offset:33792
	ds_read_b128 v[216:219], v155 offset:34816
	ds_read_b128 v[220:223], v155 offset:35840
	ds_read_b128 v[224:227], v155 offset:36864
	ds_read_b128 v[228:231], v155 offset:37888
	ds_read_b128 v[232:235], v155 offset:38912
	ds_read_b128 v[236:239], v155 offset:39936
	global_load_lds_dwordx4 v[200:201], off
	v_lshl_add_u64 v[200:201], s[18:19], 0, v[140:141]
	s_mov_b32 m0, s49
	s_nop 0
	global_load_lds_dwordx4 v[200:201], off
	s_waitcnt vmcnt(8)
	s_waitcnt lgkmcnt(0)
	s_barrier
	s_setprio 1
	s_waitcnt lgkmcnt(0)
	v_mfma_f32_16x16x32_bf16 v[128:131], v[156:159], v[208:211], v[128:131]
	v_mfma_f32_16x16x32_bf16 v[120:123], v[164:167], v[208:211], v[120:123]
	v_mfma_f32_16x16x32_bf16 v[112:115], v[156:159], v[216:219], v[112:115]
	v_mfma_f32_16x16x32_bf16 v[104:107], v[164:167], v[216:219], v[104:107]
	v_mfma_f32_16x16x32_bf16 v[96:99], v[156:159], v[224:227], v[96:99]
	v_mfma_f32_16x16x32_bf16 v[88:91], v[164:167], v[224:227], v[88:91]
	v_mfma_f32_16x16x32_bf16 v[80:83], v[156:159], v[232:235], v[80:83]
	v_mfma_f32_16x16x32_bf16 v[72:75], v[164:167], v[232:235], v[72:75]
	v_mfma_f32_16x16x32_bf16 v[128:131], v[160:163], v[212:215], v[128:131]
	v_mfma_f32_16x16x32_bf16 v[120:123], v[168:171], v[212:215], v[120:123]
	v_mfma_f32_16x16x32_bf16 v[112:115], v[160:163], v[220:223], v[112:115]
	v_mfma_f32_16x16x32_bf16 v[104:107], v[168:171], v[220:223], v[104:107]
	v_mfma_f32_16x16x32_bf16 v[96:99], v[160:163], v[228:231], v[96:99]
	v_mfma_f32_16x16x32_bf16 v[88:91], v[168:171], v[228:231], v[88:91]
	v_mfma_f32_16x16x32_bf16 v[80:83], v[160:163], v[236:239], v[80:83]
	v_mfma_f32_16x16x32_bf16 v[72:75], v[168:171], v[236:239], v[72:75]
	s_setprio 0
	s_setprio 1
	v_mfma_f32_16x16x32_bf16 v[124:127], v[172:175], v[208:211], v[124:127]
	v_mfma_f32_16x16x32_bf16 v[116:119], v[180:183], v[208:211], v[116:119]
	v_mfma_f32_16x16x32_bf16 v[108:111], v[172:175], v[216:219], v[108:111]
	v_mfma_f32_16x16x32_bf16 v[100:103], v[180:183], v[216:219], v[100:103]
	v_mfma_f32_16x16x32_bf16 v[92:95], v[172:175], v[224:227], v[92:95]
	v_mfma_f32_16x16x32_bf16 v[84:87], v[180:183], v[224:227], v[84:87]
	v_mfma_f32_16x16x32_bf16 v[76:79], v[172:175], v[232:235], v[76:79]
	v_mfma_f32_16x16x32_bf16 v[68:71], v[180:183], v[232:235], v[68:71]
	v_mfma_f32_16x16x32_bf16 v[124:127], v[176:179], v[212:215], v[124:127]
	v_mfma_f32_16x16x32_bf16 v[116:119], v[184:187], v[212:215], v[116:119]
	v_mfma_f32_16x16x32_bf16 v[108:111], v[176:179], v[220:223], v[108:111]
	v_mfma_f32_16x16x32_bf16 v[100:103], v[184:187], v[220:223], v[100:103]
	v_mfma_f32_16x16x32_bf16 v[92:95], v[176:179], v[228:231], v[92:95]
	v_mfma_f32_16x16x32_bf16 v[84:87], v[184:187], v[228:231], v[84:87]
	v_mfma_f32_16x16x32_bf16 v[76:79], v[176:179], v[236:239], v[76:79]
	v_mfma_f32_16x16x32_bf16 v[68:71], v[184:187], v[236:239], v[68:71]
	s_setprio 0
	s_barrier
	s_add_i32 s18, s46, s28
	v_lshl_add_u64 v[148:149], v[148:149], 0, s[92:93]
	s_mov_b32 m0, s18
	ds_read_b128 v[208:211], v155 offset:49152
	ds_read_b128 v[212:215], v155 offset:50176
	ds_read_b128 v[216:219], v155 offset:51200
	ds_read_b128 v[220:223], v155 offset:52224
	ds_read_b128 v[224:227], v155 offset:53248
	ds_read_b128 v[228:231], v155 offset:54272
	ds_read_b128 v[232:235], v155 offset:55296
	ds_read_b128 v[236:239], v155 offset:56320
	global_load_lds_dwordx4 v[148:149], off
	s_add_i32 m0, s18, 0x2000
	s_add_u32 s18, s22, 0x40080
	v_lshl_add_u64 v[148:149], v[188:189], 0, s[92:93]
	s_addc_u32 s19, s23, 0
	s_add_i32 s22, s47, s28
	global_load_lds_dwordx4 v[148:149], off
	v_lshl_add_u64 v[148:149], s[18:19], 0, v[2:3]
	s_mov_b32 m0, s22
	s_nop 0
	global_load_lds_dwordx4 v[148:149], off
	v_lshl_add_u64 v[148:149], s[18:19], 0, v[142:143]
	s_add_i32 m0, s22, 0x2000
	s_nop 0
	global_load_lds_dwordx4 v[148:149], off
	v_lshl_add_u64 v[148:149], v[196:197], 0, s[92:93]
	s_mov_b32 m0, s50
	s_nop 0
	global_load_lds_dwordx4 v[148:149], off
	v_lshl_add_u64 v[148:149], v[198:199], 0, s[92:93]
	s_mov_b32 m0, s51
	s_nop 0
	global_load_lds_dwordx4 v[148:149], off
	s_waitcnt vmcnt(8)
	s_waitcnt lgkmcnt(0)
	s_barrier
	s_setprio 1
	s_waitcnt lgkmcnt(0)
	v_mfma_f32_16x16x32_bf16 v[64:67], v[156:159], v[208:211], v[64:67]
	v_mfma_f32_16x16x32_bf16 v[56:59], v[164:167], v[208:211], v[56:59]
	v_mfma_f32_16x16x32_bf16 v[48:51], v[156:159], v[216:219], v[48:51]
	v_mfma_f32_16x16x32_bf16 v[40:43], v[164:167], v[216:219], v[40:43]
	v_mfma_f32_16x16x32_bf16 v[32:35], v[156:159], v[224:227], v[32:35]
	v_mfma_f32_16x16x32_bf16 v[24:27], v[164:167], v[224:227], v[24:27]
	v_mfma_f32_16x16x32_bf16 v[16:19], v[156:159], v[232:235], v[16:19]
	v_mfma_f32_16x16x32_bf16 v[8:11], v[164:167], v[232:235], v[8:11]
	v_mfma_f32_16x16x32_bf16 v[64:67], v[160:163], v[212:215], v[64:67]
	v_mfma_f32_16x16x32_bf16 v[56:59], v[168:171], v[212:215], v[56:59]
	v_mfma_f32_16x16x32_bf16 v[48:51], v[160:163], v[220:223], v[48:51]
	v_mfma_f32_16x16x32_bf16 v[40:43], v[168:171], v[220:223], v[40:43]
	v_mfma_f32_16x16x32_bf16 v[32:35], v[160:163], v[228:231], v[32:35]
	v_mfma_f32_16x16x32_bf16 v[24:27], v[168:171], v[228:231], v[24:27]
	v_mfma_f32_16x16x32_bf16 v[16:19], v[160:163], v[236:239], v[16:19]
	v_mfma_f32_16x16x32_bf16 v[8:11], v[168:171], v[236:239], v[8:11]
	s_setprio 0
	s_setprio 1
	v_mfma_f32_16x16x32_bf16 v[60:63], v[172:175], v[208:211], v[60:63]
	v_mfma_f32_16x16x32_bf16 v[52:55], v[180:183], v[208:211], v[52:55]
	v_mfma_f32_16x16x32_bf16 v[44:47], v[172:175], v[216:219], v[44:47]
	v_mfma_f32_16x16x32_bf16 v[36:39], v[180:183], v[216:219], v[36:39]
	v_mfma_f32_16x16x32_bf16 v[28:31], v[172:175], v[224:227], v[28:31]
	v_mfma_f32_16x16x32_bf16 v[20:23], v[180:183], v[224:227], v[20:23]
	v_mfma_f32_16x16x32_bf16 v[12:15], v[172:175], v[232:235], v[12:15]
	v_mfma_f32_16x16x32_bf16 v[4:7], v[180:183], v[232:235], v[4:7]
	v_mfma_f32_16x16x32_bf16 v[60:63], v[176:179], v[212:215], v[60:63]
	v_mfma_f32_16x16x32_bf16 v[52:55], v[184:187], v[212:215], v[52:55]
	v_mfma_f32_16x16x32_bf16 v[44:47], v[176:179], v[220:223], v[44:47]
	v_mfma_f32_16x16x32_bf16 v[36:39], v[184:187], v[220:223], v[36:39]
	v_mfma_f32_16x16x32_bf16 v[28:31], v[176:179], v[228:231], v[28:31]
	v_mfma_f32_16x16x32_bf16 v[20:23], v[184:187], v[228:231], v[20:23]
	v_mfma_f32_16x16x32_bf16 v[12:15], v[176:179], v[236:239], v[12:15]
	v_mfma_f32_16x16x32_bf16 v[4:7], v[184:187], v[236:239], v[4:7]
	s_setprio 0
	s_barrier
	s_add_i32 s15, s15, 2
	s_add_u32 s44, s44, 0x100
	s_addc_u32 s45, s45, 0
	s_add_u32 s13, s13, 0x100
	s_addc_u32 s14, s14, 0
	s_cmp_gt_u32 s15, 13
	s_cbranch_scc0 .LBB0_98
	s_and_b64 vcc, exec, s[2:3]
	s_cbranch_vccz .LBB0_101
	s_barrier
